# preporder + gemm3-slot conversion loop: serialising vmcnt waits removed (16 loads in flight) + all R items of layers 1..3 converted there (prologue 28544 -> 16352 items)
# speedup vs baseline: 1.0134x; 1.0028x over previous
; #define CV_MAP(g_, l_, it_) do { (l_) = lfix; \
;         if (MODE == 2) (it_) = CV_S0 + base + (g_); \
;         else if (MODE == 1) (it_) = cv_ritem(g_); \
;         else if ((g_) < CV_NR) (it_) = cv_ritem(g_); \
;         else { const int q_ = ((g_) - CV_NR) / CV_RPRO; (l_) = 1 + q_; (it_) = cv_ritem(CV_DEFER + ((g_) - CV_NR) - q_ * CV_RPRO); } } while (0)
; __device__ __forceinline__ void p0_item_load(const float* W, int N, int item, int lane, f32x4 (&wv)[8]) {
;     const int nblk = N / 32, kb = item / nblk, nb = item % nblk, k0 = 64 * kb, n0 = 32 * nb;
; #pragma unroll
;     for (int i = 0; i < 8; ++i) wv[i] = *(const f32x4*)(W + (size_t)(k0 + 8 * i + (lane >> 3)) * N + n0 + 4 * (lane & 7));
; template <int MODE>
; __device__ __forceinline__ void cv_jobs(const Frame& F, const Args& a, int lfix, int base, int njobs, int w, int nw) {
;     ...
;     for (int g = w; g < njobs; g += 2 * nw) {
;         const int g1 = g + nw; int l, it, l1, it1; CV_MAP(g, l, it); CV_MAP(g1, l1, it1);
;         cv_load(a, l, it, F.lane, sa);
;         if (g1 < njobs) cv_load(a, l1, it1, F.lane, sb);
;         cv_store(a, sa, scr, l, it, F.lane);
;         if (g1 < njobs) cv_store(a, sb, scr, l1, it1, F.lane);
.LBB0_984:
	s_addk_i32 s8, 0x800
	s_cmpk_lt_i32 s9, 0x37e0
	s_cbranch_scc0 .LBB0_1036
.LBB0_985:
	s_add_i32 s9, s8, 0x3e20
	s_add_i32 s2, s8, 0x5c60
	s_cmpk_lt_i32 s9, 0x1fe0
	s_cselect_b32 s10, s9, s2
	s_cmpk_gt_i32 s10, 0x161f
	s_cselect_b64 s[2:3], -1, 0
	s_mov_b64 s[4:5], -1
	s_and_b64 vcc, exec, s[2:3]
	s_cbranch_vccz .LBB0_995
	s_cmpk_gt_u32 s10, 0x1e1f
	s_cbranch_scc0 .LBB0_992
	s_cmpk_gt_u32 s10, 0x3e1f
	s_cbranch_scc0 .LBB0_989
	s_add_i32 s4, s10, 0xffffc1e0
	s_and_b32 s5, s4, 0xffffffc0
	v_add_u32_e32 v32, s5, v80
	s_lshl_b32 s4, s4, 7
	s_and_b32 s84, s4, 0x1f80
	v_ashrrev_i32_e32 v33, 31, v32
	v_lshl_add_u64 v[34:35], v[64:65], 0, s[84:85]
	v_lshlrev_b64 v[32:33], 13, v[32:33]
	v_lshl_add_u64 v[60:61], v[34:35], 0, v[32:33]
	v_add_co_u32_e32 v32, vcc, 0x10000, v60
	s_mov_b64 s[4:5], 0
	s_nop 0
	v_addc_co_u32_e32 v33, vcc, 0, v61, vcc
	v_add_co_u32_e32 v40, vcc, 0x20000, v60
	global_load_dwordx4 v[36:39], v[60:61], off nt
	s_nop 0
	global_load_dwordx4 v[32:35], v[32:33], off nt
	v_addc_co_u32_e32 v41, vcc, 0, v61, vcc
	v_add_co_u32_e32 v42, vcc, 0x30000, v60
	s_nop 1
	v_addc_co_u32_e32 v43, vcc, 0, v61, vcc
	v_add_co_u32_e32 v48, vcc, s90, v60
	global_load_dwordx4 v[44:47], v[40:41], off nt
	s_nop 0
	global_load_dwordx4 v[40:43], v[42:43], off nt
	v_addc_co_u32_e32 v49, vcc, 0, v61, vcc
	v_add_co_u32_e32 v50, vcc, 0x50000, v60
	s_nop 1
	v_addc_co_u32_e32 v51, vcc, 0, v61, vcc
	v_add_co_u32_e32 v56, vcc, 0x60000, v60
	global_load_dwordx4 v[52:55], v[48:49], off nt
	s_nop 0
	global_load_dwordx4 v[48:51], v[50:51], off nt
	v_addc_co_u32_e32 v57, vcc, 0, v61, vcc
	global_load_dwordx4 v[56:59], v[56:57], off nt
	v_lshl_add_u64 v[60:61], v[60:61], 0, s[18:19]
.LBB0_989:
	s_andn2_b64 vcc, exec, s[4:5]
	s_cbranch_vccnz .LBB0_991
	s_add_i32 s4, s10, 0xffffe1e0
	s_bfe_u32 s5, s4, 0x80008
	v_lshl_add_u32 v32, s5, 6, v80
	s_lshl_b32 s4, s4, 7
	s_and_b32 s84, s4, 0x7f80
	v_ashrrev_i32_e32 v33, 31, v32
	v_lshl_add_u64 v[34:35], v[66:67], 0, s[84:85]
	v_lshlrev_b64 v[32:33], 15, v[32:33]
	v_lshl_add_u64 v[60:61], v[34:35], 0, v[32:33]
	v_add_co_u32_e32 v32, vcc, 0x40000, v60
	s_nop 1
	v_addc_co_u32_e32 v33, vcc, 0, v61, vcc
	v_add_co_u32_e32 v40, vcc, 0x80000, v60
	global_load_dwordx4 v[36:39], v[60:61], off nt
	s_nop 0
	global_load_dwordx4 v[32:35], v[32:33], off nt
	v_addc_co_u32_e32 v41, vcc, 0, v61, vcc
	v_add_co_u32_e32 v42, vcc, 0xc0000, v60
	s_nop 1
	v_addc_co_u32_e32 v43, vcc, 0, v61, vcc
	v_add_co_u32_e32 v48, vcc, s73, v60
	global_load_dwordx4 v[44:47], v[40:41], off nt
	s_nop 0
	global_load_dwordx4 v[40:43], v[42:43], off nt
	v_addc_co_u32_e32 v49, vcc, 0, v61, vcc
	v_add_co_u32_e32 v50, vcc, 0x140000, v60
	s_nop 1
	v_addc_co_u32_e32 v51, vcc, 0, v61, vcc
	v_add_co_u32_e32 v56, vcc, 0x180000, v60
	global_load_dwordx4 v[52:55], v[48:49], off nt
	s_nop 0
	global_load_dwordx4 v[48:51], v[50:51], off nt
	v_addc_co_u32_e32 v57, vcc, 0, v61, vcc
	global_load_dwordx4 v[56:59], v[56:57], off nt
	v_lshl_add_u64 v[60:61], v[60:61], 0, s[16:17]

; __device__ __forceinline__ void p0_item_load(const float* W, int N, int item, int lane, f32x4 (&wv)[8]) {
;     const int nblk = N / 32, kb = item / nblk, nb = item % nblk, k0 = 64 * kb, n0 = 32 * nb;
; #pragma unroll
;     for (int i = 0; i < 8; ++i) wv[i] = *(const f32x4*)(W + (size_t)(k0 + 8 * i + (lane >> 3)) * N + n0 + 4 * (lane & 7));
; __device__ __forceinline__ void cv_load(const Args& a, int l, int it, int lane, f32x4 (&wv)[8]) {
;     ...
;     else if (it < CV_B) p0_item_load(a.in[I_WOUT] + (size_t)l * DM * DM, DM, it - CV_A, lane, wv);
.LBB0_992:
	s_andn2_b64 vcc, exec, s[4:5]
	s_cbranch_vccnz .LBB0_994
	s_add_i32 s4, s10, 0xffffe9e0
	s_and_b32 s5, s4, 0xffc0
	v_add_u32_e32 v32, s5, v80
	s_lshl_b32 s4, s4, 7
	s_and_b32 s84, s4, 0x1f80
	v_ashrrev_i32_e32 v33, 31, v32
	v_lshl_add_u64 v[34:35], v[68:69], 0, s[84:85]
	v_lshlrev_b64 v[32:33], 13, v[32:33]
	v_lshl_add_u64 v[60:61], v[34:35], 0, v[32:33]
	v_add_co_u32_e32 v32, vcc, 0x10000, v60
	s_nop 1
	v_addc_co_u32_e32 v33, vcc, 0, v61, vcc
	v_add_co_u32_e32 v40, vcc, 0x20000, v60
	global_load_dwordx4 v[36:39], v[60:61], off nt
	s_nop 0
	global_load_dwordx4 v[32:35], v[32:33], off nt
	v_addc_co_u32_e32 v41, vcc, 0, v61, vcc
	v_add_co_u32_e32 v42, vcc, 0x30000, v60
	s_nop 1
	v_addc_co_u32_e32 v43, vcc, 0, v61, vcc
	v_add_co_u32_e32 v48, vcc, s90, v60
	global_load_dwordx4 v[44:47], v[40:41], off nt
	s_nop 0
	global_load_dwordx4 v[40:43], v[42:43], off nt
	v_addc_co_u32_e32 v49, vcc, 0, v61, vcc
	v_add_co_u32_e32 v50, vcc, 0x50000, v60
	s_nop 1
	v_addc_co_u32_e32 v51, vcc, 0, v61, vcc
	v_add_co_u32_e32 v56, vcc, 0x60000, v60
	global_load_dwordx4 v[52:55], v[48:49], off nt
	s_nop 0
	global_load_dwordx4 v[48:51], v[50:51], off nt
	v_addc_co_u32_e32 v57, vcc, 0, v61, vcc
	global_load_dwordx4 v[56:59], v[56:57], off nt
	v_lshl_add_u64 v[60:61], v[60:61], 0, s[18:19]

; #define CV_MAP(g_, l_, it_) do { (l_) = lfix; \
;         if (MODE == 2) (it_) = CV_S0 + base + (g_); \
;         else if (MODE == 1) (it_) = cv_ritem(g_); \
;         else if ((g_) < CV_NR) (it_) = cv_ritem(g_); \
;         else { const int q_ = ((g_) - CV_NR) / CV_RPRO; (l_) = 1 + q_; (it_) = cv_ritem(CV_DEFER + ((g_) - CV_NR) - q_ * CV_RPRO); } } while (0)
; __device__ __forceinline__ void p0_item_load(const float* W, int N, int item, int lane, f32x4 (&wv)[8]) {
;     const int nblk = N / 32, kb = item / nblk, nb = item % nblk, k0 = 64 * kb, n0 = 32 * nb;
; #pragma unroll
;     for (int i = 0; i < 8; ++i) wv[i] = *(const f32x4*)(W + (size_t)(k0 + 8 * i + (lane >> 3)) * N + n0 + 4 * (lane & 7));
; template <int MODE>
; __device__ __forceinline__ void cv_jobs(const Frame& F, const Args& a, int lfix, int base, int njobs, int w, int nw) {
;     ...
;         const int g1 = g + nw; int l, it, l1, it1; CV_MAP(g, l, it); CV_MAP(g1, l1, it1);
;         cv_load(a, l, it, F.lane, sa);
;         if (g1 < njobs) cv_load(a, l1, it1, F.lane, sb);
.LBB0_995:
	s_andn2_b64 vcc, exec, s[4:5]
	s_mul_hi_i32 s13, s10, 0xb92143fb
	s_cbranch_vccnz .LBB0_997
	s_add_i32 s4, s13, s10
	s_lshr_b32 s5, s4, 31
	s_ashr_i32 s4, s4, 7
	s_add_i32 s5, s4, s5
	s_mul_i32 s4, s5, 0xb1
	s_sub_i32 s4, s10, s4
	s_lshl_b32 s4, s4, 5
	v_lshl_add_u32 v62, s5, 6, v80
	s_ashr_i32 s5, s4, 31
	v_lshl_add_u64 v[60:61], s[4:5], 2, v[70:71]
	v_add_u32_e32 v34, 8, v62
	v_add_u32_e32 v40, 16, v62
	v_add_u32_e32 v42, 24, v62
	v_add_u32_e32 v48, 32, v62
	v_add_u32_e32 v50, 40, v62
	v_add_u32_e32 v56, 48, v62
	v_mad_i64_i32 v[32:33], s[4:5], v62, s14, v[60:61]
	v_mad_i64_i32 v[34:35], s[4:5], v34, s14, v[60:61]
	v_mad_i64_i32 v[40:41], s[4:5], v40, s14, v[60:61]
	v_mad_i64_i32 v[42:43], s[4:5], v42, s14, v[60:61]
	v_mad_i64_i32 v[48:49], s[4:5], v48, s14, v[60:61]
	v_mad_i64_i32 v[50:51], s[4:5], v50, s14, v[60:61]
	v_mad_i64_i32 v[56:57], s[4:5], v56, s14, v[60:61]
	global_load_dwordx4 v[36:39], v[32:33], off nt
	s_nop 0
	global_load_dwordx4 v[32:35], v[34:35], off nt
	s_nop 0
	global_load_dwordx4 v[44:47], v[40:41], off nt
	s_nop 0
	global_load_dwordx4 v[40:43], v[42:43], off nt
	s_nop 0
	global_load_dwordx4 v[52:55], v[48:49], off nt
	s_nop 0
	global_load_dwordx4 v[48:51], v[50:51], off nt
	v_add_u32_e32 v62, 56, v62
	global_load_dwordx4 v[56:59], v[56:57], off nt
	v_mad_i64_i32 v[60:61], s[4:5], v62, s14, v[60:61]
.LBB0_997:
	global_load_dwordx4 v[60:63], v[60:61], off nt
	s_cmpk_lt_i32 s9, 0x1be0
	s_movk_i32 s4, 0x2240
	s_cselect_b32 s12, 0x400, s4
	s_add_i32 s12, s12, s8
	s_add_i32 s11, s12, 0x3e20
	s_cmpk_lt_i32 s9, 0x3be0
	s_cselect_b64 s[4:5], -1, 0
	s_cmpk_gt_i32 s9, 0x3bdf
	s_cbranch_scc1 .LBB0_1013
	s_cmpk_gt_i32 s11, 0x161f
	s_mov_b64 s[6:7], -1
	s_cbranch_scc0 .LBB0_1008
	s_cmpk_gt_u32 s11, 0x1e1f
	s_cbranch_scc0 .LBB0_1005
	s_cmpk_gt_u32 s11, 0x3e1f
	s_cbranch_scc0 .LBB0_1002
	s_and_b32 s6, s12, 0xffffffc0
	v_add_u32_e32 v0, s6, v80
	s_lshl_b32 s6, s12, 7
	s_and_b32 s84, s6, 0x1f80
	v_ashrrev_i32_e32 v1, 31, v0
	v_lshl_add_u64 v[2:3], v[64:65], 0, s[84:85]
	v_lshlrev_b64 v[0:1], 13, v[0:1]
	v_lshl_add_u64 v[0:1], v[2:3], 0, v[0:1]
	s_mov_b64 s[6:7], 0x10000
	v_lshl_add_u64 v[4:5], v[0:1], 0, s[6:7]
	s_mov_b64 s[6:7], 0x20000
	v_lshl_add_u64 v[8:9], v[0:1], 0, s[6:7]
	s_mov_b64 s[6:7], 0x30000
	v_lshl_add_u64 v[12:13], v[0:1], 0, s[6:7]
	s_mov_b64 s[6:7], 0x50000
	v_lshl_add_u64 v[20:21], v[0:1], 0, s[6:7]
	s_mov_b64 s[6:7], 0x60000
	v_lshl_add_u64 v[16:17], v[0:1], 0, s[88:89]
	v_lshl_add_u64 v[24:25], v[0:1], 0, s[6:7]
	v_lshl_add_u64 v[28:29], v[0:1], 0, s[18:19]
	s_mov_b64 s[6:7], 0
